# v48 with every workgroup running its split-K piece first (no XCD-group piece-position offset) now that the wave halves are staggered
# baseline (speedup 1.0000x reference)
.LBB0_1988:
	s_or_b64 exec, exec, s[0:1]
	v_readlane_b32 s16, v254, 21
	v_cndmask_b32_e64 v238, 0, 1, s[60:61]
	v_readlane_b32 s17, v254, 22
	v_cmp_ne_u32_e64 s[6:7], 1, v238
	s_andn2_b64 vcc, exec, s[60:61]
	s_mov_b64 s[12:13], -1
	s_waitcnt lgkmcnt(0)
	s_barrier
	s_cbranch_vccnz .LBB0_1990
	v_readlane_b32 s0, v254, 57
	s_lshr_b32 s0, s0, 29
	s_add_i32 s0, s91, s0
	s_bfe_u32 s0, s0, 0x10003
	s_cmp_eq_u32 s0, 0
	s_mov_b64 s[12:13], -1

.LBB0_2253:
	s_or_b64 exec, exec, s[2:3]
	v_readlane_b32 s2, v254, 21
	v_readlane_b32 s3, v254, 22
	s_and_b64 vcc, exec, s[6:7]
	s_mov_b64 s[12:13], -1
	s_waitcnt lgkmcnt(0)
	s_barrier
	s_cbranch_vccnz .LBB0_2255
	s_lshr_b32 s2, s91, 31
	s_add_i32 s2, s91, s2
	s_bfe_u32 s2, s2, 0x10001
	s_cmp_eq_u32 s2, 0
	s_mov_b64 s[12:13], -1

.LBB0_2421:
	s_or_b64 exec, exec, s[4:5]
	v_readlane_b32 s4, v254, 21
	v_readlane_b32 s5, v254, 22
	s_and_b64 vcc, exec, s[6:7]
	s_mov_b64 s[8:9], -1
	s_waitcnt lgkmcnt(0)
	s_barrier
	s_cbranch_vccnz .LBB0_2423
	v_readlane_b32 s4, v254, 57
	s_lshr_b32 s4, s4, 29
	s_add_i32 s4, s91, s4
	s_bfe_u32 s4, s4, 0x10003
	s_cmp_eq_u32 s4, 0
	s_mov_b64 s[8:9], -1
